# ssd_seq loop: vmcnt counts made store-aware (no waiting on the step's own 2-byte store acks or on the next step's first loads)
# speedup vs baseline: 1.0019x; 1.0019x over previous
; __device__ void ssd_seq(const KP& p, int l, int s, int h, int ph) {
;     ...
;   const unsigned coff = (unsigned)(((ti * 16 + fr) * NIN + 1280 + g * 128 + fq * 8) * 2);
;   unsigned xoff[2];
; #pragma unroll
;   for (int pt = 0; pt < 2; ++pt) xoff[pt] = (unsigned)(((ph * 32 + pt * 16 + fr) * NIN + 512 + h * 64 + fq * 8) * 2);
;   const unsigned boff = (unsigned)((((nB >> 1)) * NIN + 1024 + g * 128 + (nB & 1) * 64 + fq * 8) * 2);
;   const unsigned zoff = (unsigned)(((ti * 16 + fq * 4) * NIN + zc) * 2);
;   const unsigned yoff = (unsigned)(((ti * 16 + fq * 4) * DM + zc) * 2);
;   const unsigned cuoff = (unsigned)(((ti * 16 + fq * 4) * 8 + h) * 4);
;     ...
;   for (int k = 0; k < 2; ++k) SSD_LOAD(k, row0 + min(k, nch - 1) * 64);
.LBB0_402:
	s_lshl_b32 s0, s3, 6
	v_and_b32_e32 v107, 15, v0
	s_waitcnt vmcnt(0)
	v_cvt_pk_bf16_f32 v4, v49, s0
	v_ashrrev_i32_e32 v144, 3, v0
	ds_write_b16 v3, v4 offset:4896
	v_and_b32_e32 v124, -16, v144
	s_movk_i32 s15, 0xe00
	v_or_b32_e32 v4, s85, v107
	v_lshrrev_b32_e32 v2, 1, v2
	v_or_b32_e32 v3, v124, v107
	s_lshl_b32 s14, s3, 5
	v_lshlrev_b32_e32 v51, 3, v104
	v_mul_u32_u24_e32 v4, 0xe00, v4
	v_mul_lo_u32 v2, v2, s15
	v_lshlrev_b32_e32 v0, 6, v0
	s_or_b32 s1, s0, s85
	v_and_b32_e32 v105, 16, v50
	v_mul_lo_u32 v3, v3, s15
	s_and_b32 s14, s14, 0x80
	v_or3_b32 v4, v4, v51, s0
	v_mov_b32_e32 v5, 0x400
	v_and_or_b32 v0, v0, 64, v2
	v_or3_b32 v3, v3, s14, v51
	v_lshl_add_u32 v92, v4, 1, v5
	v_or3_b32 v4, s1, v107, v105
	v_or3_b32 v0, v0, s14, v51
	s_lshl_b32 s14, s3, 2
	s_mul_i32 s1, s92, 0x1c00
	v_or_b32_e32 v111, v91, v124
	s_mul_hi_u32 s0, s92, 0x1c00
	s_add_u32 s56, s36, s1
	v_lshl_add_u32 v96, v0, 1, v171
	v_mul_lo_u32 v0, v111, s15
	s_addc_u32 s57, s37, s0
	v_mov_b32_e32 v93, v1
	v_lshl_add_u32 v94, v3, 1, v170
	v_or_b32_e32 v0, v0, v4
	v_lshl_add_u64 v[2:3], s[56:57], 0, v[92:93]
	s_mov_b64 s[60:61], 0x1c000
	v_lshlrev_b32_e32 v98, 1, v0
	v_lshlrev_b32_e32 v0, 1, v4
	v_mov_b32_e32 v99, v1
	v_lshl_add_u64 v[4:5], v[2:3], 0, s[60:61]
	v_add_co_u32_e32 v2, vcc, s94, v2
	v_lshl_or_b32 v0, v111, 11, v0
	s_mov_b32 s93, s73
	v_addc_co_u32_e32 v3, vcc, 0, v3, vcc
	v_lshl_add_u64 v[54:55], s[56:57], 0, v[98:99]
	v_lshl_add_u64 v[102:103], s[42:43], 0, v[0:1]
	s_lshl_b64 s[0:1], s[92:93], 11
	v_add_co_u32_e32 v56, vcc, s62, v54
	v_lshl_add_u64 v[52:53], v[102:103], 0, s[0:1]
	s_nop 0
	v_addc_co_u32_e32 v57, vcc, 0, v55, vcc
	v_add_co_u32_e32 v58, vcc, s62, v52
	s_movk_i32 s60, 0x3000
	s_nop 0
	v_addc_co_u32_e32 v59, vcc, 0, v53, vcc
	v_add_co_u32_e32 v60, vcc, s60, v54
	s_lshl_b64 s[58:59], s[92:93], 5
	s_nop 0
	v_addc_co_u32_e32 v61, vcc, 0, v55, vcc
	s_add_u32 s58, s78, s58
	v_add_co_u32_e32 v54, vcc, 0x5000, v54
	s_waitcnt lgkmcnt(0)
	s_barrier
	v_mov_b32_e32 v62, s14
	v_lshl_or_b32 v100, v111, 5, s14
	global_load_dwordx4 v[34:37], v94, s[56:57] offset:64
	global_load_dwordx4 v[30:33], v94, s[56:57] offset:128
	global_load_dwordx4 v[26:29], v94, s[56:57] offset:192
	global_load_dwordx4 v[22:25], v92, s[56:57]
	global_load_dwordx4 v[18:21], v92, s[56:57] offset:64
	global_load_dwordx4 v[6:9], v[2:3], off
	s_nop 0
	global_load_dwordx4 v[2:5], v[4:5], off offset:64
	s_nop 0
	global_load_dwordx4 v[38:41], v94, s[56:57]
	global_load_dwordx4 v[10:13], v96, s[56:57] offset:64
	s_addc_u32 s59, s79, s59
	global_load_dwordx4 v[14:17], v96, s[56:57]
	global_load_ushort v128, v98, s[56:57]
	v_addc_co_u32_e32 v55, vcc, 0, v55, vcc
	global_load_ushort v129, v[52:53], off
	global_load_ushort v125, v[52:53], off offset:2048
	global_load_ushort v126, v[56:57], off offset:3072
	global_load_ushort v119, v[58:59], off
	global_load_ushort v120, v[60:61], off offset:2048
	global_load_ushort v117, v[54:55], off offset:1024
	global_load_ushort v116, v[58:59], off offset:2048
	global_load_dword v130, v100, s[58:59]
	global_load_dword v127, v100, s[58:59] offset:32
	global_load_dword v123, v100, s[58:59] offset:64
	global_load_dword v118, v100, s[58:59] offset:96
	global_load_dword v112, v62, s[58:59] offset:2016
	v_and_b32_e32 v90, -16, v50
	s_movk_i32 s15, 0x110
	v_mul_u32_u24_e32 v108, 0x440, v104
	s_mov_b32 s3, 0
	s_andn2_b64 vcc, exec, s[38:39]
	v_mul_u32_u24_e32 v113, 0x110, v107
	v_lshlrev_b32_e32 v109, 1, v90
	v_lshlrev_b32_e32 v110, 1, v107
	v_lshlrev_b32_e32 v114, 1, v51
	v_mad_u32_u24 v115, v105, s15, 0
	s_cbranch_vccnz .LBB0_406
	s_add_i32 s15, s87, -1
	s_add_i32 s72, s15, s92
	s_and_b32 s58, s2, 0x1c0
	s_and_b32 s59, s82, 32
	s_lshl_b64 s[2:3], s[72:73], 5
	s_add_u32 s2, s78, s2
	s_addc_u32 s3, s79, s3
	v_mov_b32_e32 v101, v1
	s_add_u32 s56, s2, s14
	s_addc_u32 s57, s3, 0
	v_lshl_add_u64 v[50:51], s[2:3], 0, v[100:101]
	s_mul_i32 s2, s72, 0x1c00
	s_mul_hi_u32 s3, s72, 0x1c00
	s_add_u32 s2, s36, s2
	s_addc_u32 s3, s37, s3
	v_lshl_add_u64 v[52:53], s[2:3], 0, v[98:99]
	s_movk_i32 s61, 0x5000
	global_load_dword v250, v1, s[56:57] offset:2016
	global_load_dword v250, v1, s[56:57] offset:2016
	global_load_dword v250, v1, s[56:57] offset:2016
	global_load_dword v250, v1, s[56:57] offset:2016
	global_load_dword v143, v1, s[56:57] offset:2016
	v_add_co_u32_e32 v54, vcc, s61, v52
	s_lshl_b64 s[56:57], s[72:73], 11
	s_nop 0
	v_addc_co_u32_e32 v55, vcc, 0, v53, vcc
	v_lshl_add_u64 v[56:57], v[102:103], 0, s[56:57]
	v_add_co_u32_e32 v58, vcc, s62, v56
	v_mov_b32_e32 v95, v1
	s_nop 0
	v_addc_co_u32_e32 v59, vcc, 0, v57, vcc
	v_add_co_u32_e32 v60, vcc, s60, v52
	v_mov_b32_e32 v97, v1
	s_nop 0
	v_addc_co_u32_e32 v61, vcc, 0, v53, vcc
	v_add_co_u32_e32 v62, vcc, s62, v52
	v_add_u32_e32 v64, 0x1c000, v92
	s_nop 0
	v_addc_co_u32_e32 v63, vcc, 0, v53, vcc
	global_load_dword v142, v[50:51], off offset:96
	global_load_dword v135, v[50:51], off offset:64
	global_load_dword v137, v[50:51], off offset:32
	global_load_dword v139, v[50:51], off
	global_load_ushort v141, v[54:55], off offset:1024
	global_load_ushort v131, v[58:59], off offset:2048
	global_load_ushort v132, v[60:61], off offset:2048
	global_load_ushort v136, v[62:63], off offset:3072
	global_load_ushort v133, v[58:59], off
	global_load_ushort v134, v[56:57], off offset:2048
	global_load_ushort v140, v[56:57], off
	global_load_ushort v138, v[52:53], off
	v_lshl_add_u64 v[50:51], s[2:3], 0, v[96:97]
	v_lshl_add_u64 v[62:63], s[2:3], 0, v[92:93]
	v_lshl_add_u64 v[86:87], s[2:3], 0, v[94:95]
	global_load_dwordx4 v[66:69], v[50:51], off offset:64
	global_load_dwordx4 v[70:73], v[50:51], off
	s_nop 0
	global_load_dwordx4 v[50:53], v64, s[2:3] offset:64
	global_load_dwordx4 v[54:57], v64, s[2:3]
	global_load_dwordx4 v[58:61], v[62:63], off offset:64
	s_nop 0
	global_load_dwordx4 v[62:65], v[62:63], off
	s_nop 0
	global_load_dwordx4 v[74:77], v[86:87], off offset:192
	global_load_dwordx4 v[78:81], v[86:87], off offset:128
	global_load_dwordx4 v[82:85], v[86:87], off offset:64
	s_nop 0
	global_load_dwordx4 v[86:89], v[86:87], off
	s_movk_i32 s2, 0x43
	v_add3_u32 v124, v124, v91, s2
	s_or_b32 s2, s58, s59
	v_lshlrev_b32_e32 v144, 11, v144
	v_or_b32_e32 v105, s2, v105
	v_and_b32_e32 v144, 0xffff8000, v144
	v_lshlrev_b32_e32 v104, 13, v104
	v_add_lshl_u32 v105, v105, v107, 1
	s_add_u32 s0, s91, s0
	v_or3_b32 v104, v144, v104, v105
	v_mov_b32_e32 v105, v1
	s_addc_u32 s1, s90, s1
	v_add3_u32 v121, 0, v109, v110
	v_add3_u32 v122, v115, v113, v114
	v_lshl_add_u64 v[104:105], s[0:1], 0, v[104:105]
	s_mov_b32 s0, 3
	s_mov_b64 s[58:59], 0x800
	s_mov_b64 s[64:65], 0x1000
	s_mov_b64 s[80:81], 0x1800
	s_mov_b64 s[70:71], 0x1c000
; __device__ void ssd_seq(const KP& p, int l, int s, int h, int ph) {
;     ...
;       SSD_LOAD(k, row0 + min(c + 2, nch - 1) * 64);
.LBB0_404:
	ds_read_b128 v[144:147], v122
	ds_read_b128 v[148:151], v122 offset:64
	ds_read_b128 v[152:155], v122 offset:128
	ds_read_b128 v[174:177], v122 offset:192
	s_mov_b32 s76, s0
	s_waitcnt vmcnt(38) lgkmcnt(3)
	v_mfma_f32_16x16x32_bf16 v[38:41], v[38:41], v[144:147], 0
	s_mov_b32 s0, 0xfffe0000
	s_mov_b32 s1, -1
	v_add_u32_e32 v145, v121, v108
	s_waitcnt lgkmcnt(2)
	v_mfma_f32_16x16x32_bf16 v[34:37], v[34:37], v[148:151], 0
	v_add_u32_e32 v144, v121, v106
	s_waitcnt lgkmcnt(1)
	v_mfma_f32_16x16x32_bf16 v[30:33], v[30:33], v[152:155], v[38:41]
	s_waitcnt lgkmcnt(0)
	v_mfma_f32_16x16x32_bf16 v[26:29], v[26:29], v[174:177], v[34:37]
	s_waitcnt vmcnt(27)
	s_nop 1
	v_mul_f32_e32 v34, 0x3fb8aa3b, v130
	v_exp_f32_e32 v34, v34
	s_nop 2
	v_pk_add_f32 v[28:29], v[32:33], v[28:29]
	v_pk_add_f32 v[26:27], v[30:31], v[26:27]
	v_lshlrev_b32_e32 v33, 16, v129
	v_fmac_f32_e32 v33, v34, v26
	v_lshlrev_b32_e32 v26, 16, v128
	v_mul_f32_e32 v34, 0xbfb8aa3b, v26
	v_exp_f32_e32 v34, v34
	v_add_u32_e32 v32, 0xffffffbd, v124
	v_lshl_add_u64 v[30:31], v[104:105], 0, s[0:1]
	v_cmp_gt_i32_e32 vcc, s86, v32
	v_add_f32_e32 v34, 1.0, v34
	v_rcp_f32_e32 v34, v34
	s_nop 0
	v_mul_f32_e32 v26, v34, v26
	v_mul_f32_e32 v26, v26, v33
	v_cvt_pk_bf16_f32 v26, v26, s0
	v_and_b32_e32 v26, 0xffff, v26
	v_cndmask_b32_e32 v26, 0, v26, vcc
	global_store_short v[30:31], v26, off
	s_waitcnt vmcnt(28)
	v_mul_f32_e32 v30, 0x3fb8aa3b, v127
	v_exp_f32_e32 v30, v30
	v_lshlrev_b32_e32 v26, 16, v125
	s_mov_b32 s0, 0xfffe0800
	s_mov_b32 s1, -1
	v_fmac_f32_e32 v26, v30, v27
	v_lshlrev_b32_e32 v27, 16, v126
	v_mul_f32_e32 v30, 0xbfb8aa3b, v27
	v_exp_f32_e32 v30, v30
	s_nop 0
	v_add_f32_e32 v30, 1.0, v30
	v_rcp_f32_e32 v30, v30
	s_nop 0
	v_mul_f32_e32 v27, v30, v27
	v_mul_f32_e32 v30, v27, v26
	v_add_u32_e32 v26, 0xffffffbe, v124
	v_cvt_pk_bf16_f32 v30, v30, s0
	v_cmp_gt_i32_e32 vcc, s86, v26
	v_lshl_add_u64 v[26:27], v[104:105], 0, s[0:1]
	v_and_b32_e32 v30, 0xffff, v30
	v_cndmask_b32_e32 v30, 0, v30, vcc
	global_store_short v[26:27], v30, off
	s_waitcnt vmcnt(29)
	v_mul_f32_e32 v27, 0x3fb8aa3b, v123
	v_exp_f32_e32 v27, v27
	v_lshlrev_b32_e32 v26, 16, v119
	s_mov_b32 s0, 0xfffe1000
	s_mov_b32 s1, -1
	v_fmac_f32_e32 v26, v27, v28
	v_lshlrev_b32_e32 v27, 16, v120
	v_mul_f32_e32 v28, 0xbfb8aa3b, v27
	v_exp_f32_e32 v28, v28
	s_nop 0
	v_add_f32_e32 v28, 1.0, v28
	v_rcp_f32_e32 v28, v28
	s_nop 0
	v_mul_f32_e32 v27, v28, v27
	v_mul_f32_e32 v28, v27, v26
	v_add_u32_e32 v26, 0xffffffbf, v124
	v_cvt_pk_bf16_f32 v28, v28, s0
	v_cmp_gt_i32_e32 vcc, s86, v26
	v_lshl_add_u64 v[26:27], v[104:105], 0, s[0:1]
	v_and_b32_e32 v28, 0xffff, v28
	v_cndmask_b32_e32 v28, 0, v28, vcc
	global_store_short v[26:27], v28, off
	s_waitcnt vmcnt(30)
	v_mul_f32_e32 v27, 0x3fb8aa3b, v118
	v_exp_f32_e32 v27, v27
	v_lshlrev_b32_e32 v26, 16, v116
	s_mov_b32 s0, 0xfffe1800
	s_mov_b32 s1, -1
	v_fmac_f32_e32 v26, v27, v29
	v_lshlrev_b32_e32 v27, 16, v117
	v_mul_f32_e32 v28, 0xbfb8aa3b, v27
	v_exp_f32_e32 v28, v28
	s_nop 0
	v_add_f32_e32 v28, 1.0, v28
	v_rcp_f32_e32 v28, v28
	s_nop 0
	v_mul_f32_e32 v27, v28, v27
	v_mul_f32_e32 v28, v27, v26
	v_subrev_u32_e32 v26, 64, v124
	v_cvt_pk_bf16_f32 v28, v28, s0
	v_cmp_gt_i32_e32 vcc, s86, v26
	v_lshl_add_u64 v[26:27], v[104:105], 0, s[0:1]
	v_and_b32_e32 v28, 0xffff, v28
	v_cndmask_b32_e32 v28, 0, v28, vcc
	global_store_short v[26:27], v28, off
	s_waitcnt vmcnt(31)
	v_mul_f32_e32 v26, 0x3fb8aa3b, v112
	v_exp_f32_e32 v30, v26
	s_nop 0
	v_pk_mul_f32 v[26:27], v[30:31], v[42:43] op_sel_hi:[0,1]
	v_pk_mul_f32 v[28:29], v[30:31], v[44:45] op_sel_hi:[0,1]
	s_nop 1
	v_mfma_f32_16x16x32_bf16 v[22:25], v[22:25], v[14:17], v[26:29]
	v_mfma_f32_16x16x32_bf16 v[42:45], v[18:21], v[10:13], v[22:25]
	v_mul_f32_e64 v20, v30, v48
	v_mul_f32_e64 v21, v30, v49
	s_nop 5
	v_cvt_pk_bf16_f32 v18, v42, s0
	ds_write_b16 v145, v18 offset:8704
	v_cvt_pk_bf16_f32 v18, v43, s0
	ds_write_b16 v144, v18 offset:8704
	v_cvt_pk_bf16_f32 v18, v44, s0
	ds_write_b16 v144, v18 offset:8976
	v_cvt_pk_bf16_f32 v18, v45, s0
	ds_write_b16 v144, v18 offset:9248
	v_pk_mul_f32 v[18:19], v[30:31], v[46:47] op_sel_hi:[0,1]
	s_nop 1
	v_mfma_f32_16x16x32_bf16 v[6:9], v[6:9], v[14:17], v[18:21]
	v_mfma_f32_16x16x32_bf16 v[46:49], v[2:5], v[10:13], v[6:9]
	s_nop 7
	v_cvt_pk_bf16_f32 v2, v46, s0
	ds_write_b16 v144, v2 offset:12784
	v_cvt_pk_bf16_f32 v2, v47, s0
	ds_write_b16 v144, v2 offset:13056
	v_cvt_pk_bf16_f32 v2, v48, s0
	ds_write_b16 v144, v2 offset:13328
	v_cvt_pk_bf16_f32 v2, v49, s0
	s_add_i32 s0, s76, -1
	s_min_u32 s0, s0, s15
	s_lshl_b32 s0, s0, 6
	s_add_i32 s72, s0, s92
	s_mul_i32 s0, s72, 0x1c00
	s_mul_hi_u32 s1, s72, 0x1c00
	s_add_u32 s0, s36, s0
	s_addc_u32 s1, s37, s1
	ds_write_b16 v144, v2 offset:13600
	v_lshl_add_u64 v[2:3], s[0:1], 0, v[94:95]
	global_load_dwordx4 v[38:41], v[2:3], off
	global_load_dwordx4 v[34:37], v[2:3], off offset:64
	global_load_dwordx4 v[30:33], v[2:3], off offset:128
	global_load_dwordx4 v[26:29], v[2:3], off offset:192
	v_lshl_add_u64 v[2:3], s[0:1], 0, v[92:93]
	global_load_dwordx4 v[22:25], v[2:3], off
	global_load_dwordx4 v[18:21], v[2:3], off offset:64
	v_lshl_add_u64 v[4:5], v[2:3], 0, s[70:71]
	v_add_co_u32_e32 v2, vcc, s94, v2
	s_lshl_b64 s[2:3], s[72:73], 5
	s_lshl_b64 s[56:57], s[72:73], 11
	v_addc_co_u32_e32 v3, vcc, 0, v3, vcc
	v_lshl_add_u64 v[146:147], s[0:1], 0, v[98:99]
	s_add_u32 s2, s78, s2
	v_add_co_u32_e32 v118, vcc, s62, v146
	v_lshl_add_u64 v[10:11], s[0:1], 0, v[96:97]
	s_addc_u32 s3, s79, s3
	v_lshl_add_u64 v[116:117], v[102:103], 0, s[56:57]
	v_addc_co_u32_e32 v119, vcc, 0, v147, vcc
	global_load_dwordx4 v[6:9], v[2:3], off
	s_nop 0
	global_load_dwordx4 v[2:5], v[4:5], off offset:64
	s_nop 0
	global_load_dwordx4 v[14:17], v[10:11], off
	s_nop 0
	global_load_dwordx4 v[10:13], v[10:11], off offset:64
	v_lshl_add_u64 v[148:149], s[2:3], 0, v[100:101]
	global_load_ushort v129, v[116:117], off
	global_load_ushort v128, v[146:147], off
	global_load_dword v130, v[148:149], off
	global_load_ushort v125, v[116:117], off offset:2048
	v_add_co_u32_e32 v116, vcc, s62, v116
	s_add_u32 s0, s2, s14
	s_nop 0
	v_addc_co_u32_e32 v117, vcc, 0, v117, vcc
	v_add_co_u32_e32 v150, vcc, s60, v146
	s_addc_u32 s1, s3, 0
	s_nop 0
	v_addc_co_u32_e32 v151, vcc, 0, v147, vcc
	v_add_co_u32_e32 v146, vcc, s61, v146
	global_load_ushort v126, v[118:119], off offset:3072
	global_load_dword v127, v[148:149], off offset:32
	v_addc_co_u32_e32 v147, vcc, 0, v147, vcc
	global_load_ushort v119, v[116:117], off
	global_load_ushort v120, v[150:151], off offset:2048
	global_load_dword v123, v[148:149], off offset:64
	s_nop 0
	global_load_ushort v116, v[116:117], off offset:2048
	s_nop 0
	global_load_ushort v117, v[146:147], off offset:1024
	global_load_dword v118, v[148:149], off offset:96
	global_load_dword v112, v1, s[0:1] offset:2016
	s_waitcnt lgkmcnt(0)
	s_barrier
; __device__ void ssd_seq(const KP& p, int l, int s, int h, int ph) {
;     ...
;       SSD_LOAD(k, row0 + min(c + 2, nch - 1) * 64);
	ds_read_b128 v[146:149], v122 offset:8704
	ds_read_b128 v[150:153], v122 offset:8768
	ds_read_b128 v[174:177], v122 offset:8832
	ds_read_b128 v[178:181], v122 offset:8896
	s_waitcnt vmcnt(27) lgkmcnt(3)
	v_mfma_f32_16x16x32_bf16 v[86:89], v[86:89], v[146:149], 0
	s_waitcnt lgkmcnt(2)
	v_mfma_f32_16x16x32_bf16 v[82:85], v[82:85], v[150:153], 0
	s_waitcnt lgkmcnt(1)
	v_mfma_f32_16x16x32_bf16 v[78:81], v[78:81], v[174:177], v[86:89]
	s_waitcnt lgkmcnt(0)
	v_mfma_f32_16x16x32_bf16 v[82:85], v[74:77], v[178:181], v[82:85]
	s_nop 7
	v_pk_add_f32 v[74:75], v[80:81], v[84:85]
	v_mul_f32_e32 v80, 0x3fb8aa3b, v139
	v_exp_f32_e32 v80, v80
	v_pk_add_f32 v[76:77], v[78:79], v[82:83]
	v_lshlrev_b32_e32 v79, 16, v140
	v_add_u32_e32 v78, -3, v124
	v_fmac_f32_e32 v79, v80, v76
	v_lshlrev_b32_e32 v76, 16, v138
	v_mul_f32_e32 v80, 0xbfb8aa3b, v76
	v_exp_f32_e32 v80, v80
	v_cmp_gt_i32_e32 vcc, s86, v78
	v_mul_f32_e32 v78, 0x3fb8aa3b, v137
	v_exp_f32_e32 v78, v78
	v_add_f32_e32 v80, 1.0, v80
	v_rcp_f32_e32 v80, v80
	s_nop 0
	v_mul_f32_e32 v76, v80, v76
	v_mul_f32_e32 v76, v76, v79
	v_cvt_pk_bf16_f32 v76, v76, s0
	v_and_b32_e32 v76, 0xffff, v76
	v_cndmask_b32_e32 v76, 0, v76, vcc
	global_store_short v[104:105], v76, off
	v_lshlrev_b32_e32 v76, 16, v134
	v_fmac_f32_e32 v76, v78, v77
	v_lshlrev_b32_e32 v77, 16, v136
	v_mul_f32_e32 v78, 0xbfb8aa3b, v77
	v_exp_f32_e32 v78, v78
	s_nop 0
	v_add_f32_e32 v78, 1.0, v78
	v_rcp_f32_e32 v78, v78
	s_nop 0
	v_mul_f32_e32 v77, v78, v77
	v_mul_f32_e32 v78, v77, v76
	v_add_u32_e32 v76, -2, v124
	v_cvt_pk_bf16_f32 v78, v78, s0
	v_cmp_gt_i32_e32 vcc, s86, v76
	v_lshl_add_u64 v[76:77], v[104:105], 0, s[58:59]
	v_and_b32_e32 v78, 0xffff, v78
	v_cndmask_b32_e32 v78, 0, v78, vcc
	global_store_short v[76:77], v78, off
	v_mul_f32_e32 v77, 0x3fb8aa3b, v135
	v_exp_f32_e32 v77, v77
	v_lshlrev_b32_e32 v76, 16, v133
	v_fmac_f32_e32 v76, v77, v74
	v_lshlrev_b32_e32 v74, 16, v132
	v_mul_f32_e32 v77, 0xbfb8aa3b, v74
	v_exp_f32_e32 v77, v77
	s_nop 0
	v_add_f32_e32 v77, 1.0, v77
	v_rcp_f32_e32 v77, v77
	s_nop 0
	v_mul_f32_e32 v74, v77, v74
	v_mul_f32_e32 v74, v74, v76
	v_add_u32_e32 v76, -1, v124
	v_cvt_pk_bf16_f32 v74, v74, s0
	v_cmp_gt_i32_e32 vcc, s86, v76
	v_lshl_add_u64 v[76:77], v[104:105], 0, s[64:65]
	v_and_b32_e32 v74, 0xffff, v74
	v_cndmask_b32_e32 v74, 0, v74, vcc
	global_store_short v[76:77], v74, off
	v_mul_f32_e32 v76, 0x3fb8aa3b, v142
	v_exp_f32_e32 v76, v76
	v_lshlrev_b32_e32 v74, 16, v131
	v_cmp_gt_i32_e32 vcc, s86, v124
	v_add_u32_e32 v124, 0x80, v124
	v_fmac_f32_e32 v74, v76, v75
	v_lshlrev_b32_e32 v75, 16, v141
	v_mul_f32_e32 v76, 0xbfb8aa3b, v75
	v_exp_f32_e32 v76, v76
	s_nop 0
	v_add_f32_e32 v76, 1.0, v76
	v_rcp_f32_e32 v76, v76
	s_nop 0
	v_mul_f32_e32 v75, v76, v75
	v_mul_f32_e32 v76, v75, v74
	v_cvt_pk_bf16_f32 v76, v76, s0
	v_lshl_add_u64 v[74:75], v[104:105], 0, s[80:81]
	v_and_b32_e32 v76, 0xffff, v76
	v_cndmask_b32_e32 v76, 0, v76, vcc
	global_store_short v[74:75], v76, off
	v_mul_f32_e32 v74, 0x3fb8aa3b, v143
	v_exp_f32_e32 v74, v74
	s_nop 0
	v_pk_mul_f32 v[44:45], v[74:75], v[44:45] op_sel_hi:[0,1]
	v_pk_mul_f32 v[42:43], v[74:75], v[42:43] op_sel_hi:[0,1]
	v_pk_mul_f32 v[48:49], v[74:75], v[48:49] op_sel_hi:[0,1]
	v_pk_mul_f32 v[46:47], v[74:75], v[46:47] op_sel_hi:[0,1]
	v_mfma_f32_16x16x32_bf16 v[42:45], v[62:65], v[70:73], v[42:45]
	s_nop 0
	v_mfma_f32_16x16x32_bf16 v[46:49], v[54:57], v[70:73], v[46:49]
	v_mfma_f32_16x16x32_bf16 v[42:45], v[58:61], v[66:69], v[42:45]
	v_mfma_f32_16x16x32_bf16 v[46:49], v[50:53], v[66:69], v[46:49]
	s_nop 6
	v_cvt_pk_bf16_f32 v58, v42, s0
	v_cvt_pk_bf16_f32 v50, v46, s0
	ds_write_b16 v145, v58
	v_cvt_pk_bf16_f32 v58, v43, s0
	ds_write_b16 v144, v50 offset:4080
	v_cvt_pk_bf16_f32 v50, v47, s0
	ds_write_b16 v144, v58
	v_cvt_pk_bf16_f32 v58, v44, s0
	ds_write_b16 v144, v50 offset:4352
	v_cvt_pk_bf16_f32 v50, v48, s0
	ds_write_b16 v144, v58 offset:272
	v_cvt_pk_bf16_f32 v58, v45, s0
	ds_write_b16 v144, v50 offset:4624
	v_cvt_pk_bf16_f32 v50, v49, s0
	s_min_u32 s0, s76, s15
	s_lshl_b32 s0, s0, 6
	s_add_i32 s72, s0, s92
	s_mul_i32 s1, s72, 0x1c00
	s_mul_hi_u32 s0, s72, 0x1c00
	s_add_u32 s74, s36, s1
	s_addc_u32 s75, s37, s0
	ds_write_b16 v144, v58 offset:544
	ds_write_b16 v144, v50 offset:4896
	v_lshl_add_u64 v[50:51], s[74:75], 0, v[94:95]
	global_load_dwordx4 v[86:89], v[50:51], off
	global_load_dwordx4 v[82:85], v[50:51], off offset:64
	global_load_dwordx4 v[78:81], v[50:51], off offset:128
	global_load_dwordx4 v[74:77], v[50:51], off offset:192
	v_lshl_add_u64 v[50:51], s[74:75], 0, v[92:93]
	global_load_dwordx4 v[62:65], v[50:51], off
	global_load_dwordx4 v[58:61], v[50:51], off offset:64
	v_lshl_add_u64 v[52:53], v[50:51], 0, s[70:71]
	v_add_co_u32_e32 v50, vcc, s94, v50
	v_lshl_add_u64 v[142:143], s[74:75], 0, v[98:99]
	s_nop 0
	v_addc_co_u32_e32 v51, vcc, 0, v51, vcc
	s_lshl_b64 s[2:3], s[72:73], 11
	v_add_co_u32_e32 v136, vcc, s62, v142
	v_lshl_add_u64 v[132:133], v[102:103], 0, s[2:3]
	s_nop 0
	v_addc_co_u32_e32 v137, vcc, 0, v143, vcc
	v_add_co_u32_e32 v146, vcc, s62, v132
	s_lshl_b64 s[0:1], s[72:73], 5
	s_nop 0
	v_addc_co_u32_e32 v147, vcc, 0, v133, vcc
	s_add_u32 s0, s78, s0
	v_add_co_u32_e32 v148, vcc, s60, v142
	v_lshl_add_u64 v[66:67], s[74:75], 0, v[96:97]
	s_addc_u32 s1, s79, s1
	v_addc_co_u32_e32 v149, vcc, 0, v143, vcc
	global_load_dwordx4 v[54:57], v[50:51], off
	s_nop 0
	global_load_dwordx4 v[50:53], v[52:53], off offset:64
	s_nop 0
	global_load_dwordx4 v[70:73], v[66:67], off
	s_nop 0
	global_load_dwordx4 v[66:69], v[66:67], off offset:64
	v_lshl_add_u64 v[144:145], s[0:1], 0, v[100:101]
	global_load_ushort v140, v[132:133], off
	global_load_ushort v138, v[142:143], off
	global_load_dword v139, v[144:145], off
	global_load_ushort v134, v[132:133], off offset:2048
	v_add_co_u32_e32 v142, vcc, s61, v142
	s_add_u32 s0, s0, s14
	global_load_ushort v136, v[136:137], off offset:3072
	s_nop 0
	global_load_dword v137, v[144:145], off offset:32
	global_load_ushort v133, v[146:147], off
	global_load_ushort v132, v[148:149], off offset:2048
	global_load_dword v135, v[144:145], off offset:64
	global_load_ushort v131, v[146:147], off offset:2048
	v_addc_co_u32_e32 v143, vcc, 0, v143, vcc
	s_addc_u32 s1, s1, 0
	global_load_ushort v141, v[142:143], off offset:1024
	s_nop 0
	global_load_dword v142, v[144:145], off offset:96
	global_load_dword v143, v1, s[0:1] offset:2016
	s_waitcnt lgkmcnt(0)
	s_barrier
	s_add_i32 s0, s76, 2
	s_mov_b64 s[2:3], 0x40000
	v_lshl_add_u64 v[104:105], v[104:105], 0, s[2:3]
	s_cmp_lt_u32 s76, s87
	s_cbranch_scc1 .LBB0_404
	s_add_i32 s3, s0, -3
	s_mov_b64 s[70:71], 0x17ca9100
